# GEMM phase prologues: second staging batch issued before the first wait (one DMA latency less at every phase start)
# baseline (speedup 1.0000x reference)
; #define PG8_STAGE(bufoff, gbase, voff) do { _Pragma("unroll") for (int _i = 0; _i < 2; ++_i) \
;         __builtin_amdgcn_global_load_lds((const unsigned*)((const char*)(gbase) + (voff)[_i]), (LAS unsigned*)(lds + (bufoff) + ldsw + _i * 8192), 16, 0, 0); } while (0)
; #define PG8_WAIT_V(n) asm volatile("s_waitcnt vmcnt(" #n ")" ::: "memory")
; #define PG8_BAR __builtin_amdgcn_s_barrier()
; template <class Epi, class Sched, bool ALIGN_EPI>
; __device__ __forceinline__ void gemm_phase(LAS unsigned char* lds, const Gemm g, const Sched& S, const Epi& E) {
;     ...
;     const unsigned ldsw = (unsigned)wid * 1024u;
;     const int aoff = lds_byte(wr * 64 + fr, fq * 8), boff = lds_byte(wc * 32 + fr, fq * 8);
;     ...
;     const char* cA = (const char*)g.A + (size_t)cur.pm * tstepA; const char* cB = (const char*)g.Bt + (size_t)cur.pn * tstepB;
;     PG8_STAGE(PG8_SB(0, 0), cB, voffB); PG8_STAGE(PG8_SB(0, 1), cB + hstepB, voffB); PG8_STAGE(PG8_SA(0, 0), cA, voffA); PG8_STAGE(PG8_SA(0, 1), cA + hstepA, voffA);
;     if (wr == 1) PG8_BAR;
;     PG8_WAIT_V(2); PG8_BAR;
;     PG8_STAGE(PG8_SB(1, 0), cB + kstep, voffB); PG8_STAGE(PG8_SA(1, 0), cA + kstep, voffA); PG8_STAGE(PG8_SB(1, 1), cB + hstepB + kstep, voffB);
;     PG8_WAIT_V(6); PG8_BAR;
.LBB0_601:
	s_lshl_b32 s8, s8, 5
	s_and_b32 s14, s8, 0x60
	s_mov_b64 s[8:9], 0x80
	s_add_i32 m0, s21, 0x18000
	v_lshl_add_u64 v[6:7], v[6:7], 0, s[8:9]
	s_lshl_b32 s11, s10, 13
	s_lshl_b32 s15, s14, 7
	global_load_lds_dwordx4 v[6:7], off
	v_lshl_add_u64 v[4:5], v[4:5], 0, s[8:9]
	s_add_i32 m0, s21, 0x1a000
	s_add_i32 s38, s21, 0x8000
	s_add_i32 s39, s21, 0xa000
	global_load_lds_dwordx4 v[4:5], off
	v_lshl_add_u64 v[0:1], v[0:1], 0, s[8:9]
	s_mov_b32 m0, s38
	s_add_u32 s12, s24, 0x40080
	global_load_lds_dwordx4 v[0:1], off
	v_lshl_add_u64 v[0:1], v[2:3], 0, s[8:9]
	s_mov_b32 m0, s39
	s_addc_u32 s13, s25, 0
	global_load_lds_dwordx4 v[0:1], off
	s_add_i32 m0, s21, 0x1c000
	v_lshl_add_u64 v[0:1], s[12:13], 0, v[132:133]
	global_load_lds_dwordx4 v[0:1], off
	v_lshl_add_u64 v[0:1], s[12:13], 0, v[128:129]
	s_add_i32 m0, s21, 0x1e000
	s_sext_i32_i8 s47, s2
	global_load_lds_dwordx4 v[0:1], off
	s_waitcnt vmcnt(8)
	s_barrier
	v_and_b32_e32 v0, 15, v153
	v_lshlrev_b32_e32 v1, 1, v11
	v_lshl_or_b32 v144, s10, 6, v0
	v_lshl_or_b32 v2, v0, 6, v1
	v_lshlrev_b32_e32 v0, 2, v0
	v_and_b32_e32 v3, 32, v0
	v_bitop3_b32 v2, v2, s11, v3 bitop3:0xde
	v_lshlrev_b32_e32 v3, 6, v153
	s_movk_i32 s2, 0x3c0
	v_and_or_b32 v1, v3, s2, v1
	s_lshl_b32 s2, s10, 8
	s_add_i32 s2, s2, 0
	v_lshlrev_b32_e32 v3, 2, v153
	s_add_i32 s2, s2, 0x20000
	v_and_b32_e32 v3, 32, v3
	v_add_u32_e32 v146, s2, v0
	v_lshlrev_b32_e32 v0, 8, v153
	v_bitop3_b32 v145, s15, v1, v3 bitop3:0xf6
	v_and_b32_e32 v0, 0x38000, v0
	v_lshlrev_b32_e32 v1, 11, v12
	v_or3_b32 v0, v9, v0, v1
	v_add_u32_e32 v136, v0, v10
	v_lshlrev_b32_e32 v0, 4, v8
	s_waitcnt vmcnt(6)
	s_cmpk_lt_u32 s3, 0x100
	v_and_b32_e32 v0, 0x78000, v0
	s_cselect_b64 s[10:11], -1, 0
	v_or3_b32 v0, v9, v0, v1
	s_add_i32 s40, 0, 0x10000
	s_add_i32 s41, 0, 0x14000
	v_or_b32_e32 v147, s14, v11
	v_mov_b32_e32 v137, v133
	v_add_u32_e32 v138, v0, v10
	v_mov_b32_e32 v139, v133
	v_mov_b64_e32 v[140:141], 0xb00
	v_mov_b64_e32 v[142:143], 0xaff
	v_add_u32_e32 v148, s40, v145
	v_add_u32_e32 v149, s41, v145
	v_add_u32_e32 v150, 0, v2
	s_movk_i32 s42, 0x1600
	s_mov_b32 s43, 0
	s_barrier
	s_branch .LBB0_604

; #define PG8_STAGE(bufoff, gbase, voff) do { _Pragma("unroll") for (int _i = 0; _i < 2; ++_i) \
;         __builtin_amdgcn_global_load_lds((const unsigned*)((const char*)(gbase) + (voff)[_i]), (LAS unsigned*)(lds + (bufoff) + ldsw + _i * 8192), 16, 0, 0); } while (0)
; #define PG8_WAIT_V(n) asm volatile("s_waitcnt vmcnt(" #n ")" ::: "memory")
; #define PG8_BAR __builtin_amdgcn_s_barrier()
; template <class Epi, class Sched, bool ALIGN_EPI>
; __device__ __forceinline__ void gemm_phase(LAS unsigned char* lds, const Gemm g, const Sched& S, const Epi& E) {
;     ...
;     const unsigned ldsw = (unsigned)wid * 1024u;
;     const int aoff = lds_byte(wr * 64 + fr, fq * 8), boff = lds_byte(wc * 32 + fr, fq * 8);
;     ...
;     PG8_STAGE(PG8_SB(0, 0), cB, voffB); PG8_STAGE(PG8_SB(0, 1), cB + hstepB, voffB); PG8_STAGE(PG8_SA(0, 0), cA, voffA); PG8_STAGE(PG8_SA(0, 1), cA + hstepA, voffA);
;     if (wr == 1) PG8_BAR;
;     PG8_WAIT_V(2); PG8_BAR;
;     PG8_STAGE(PG8_SB(1, 0), cB + kstep, voffB); PG8_STAGE(PG8_SA(1, 0), cA + kstep, voffA); PG8_STAGE(PG8_SB(1, 1), cB + hstepB + kstep, voffB);
;     PG8_WAIT_V(6); PG8_BAR;
.LBB0_702:
	s_add_u32 s12, s74, 0x3800000
	s_addc_u32 s13, s75, 0
	s_lshl_b32 s3, s3, 5
	s_mov_b64 s[14:15], 0x80
	s_and_b32 s18, s3, 0x60
	s_add_i32 m0, s27, 0x18000
	v_lshl_add_u64 v[6:7], v[6:7], 0, s[14:15]
	s_lshl_b32 s7, s2, 13
	s_lshl_b32 s3, s18, 7
	global_load_lds_dwordx4 v[6:7], off
	v_lshl_add_u64 v[4:5], v[4:5], 0, s[14:15]
	s_add_i32 m0, s27, 0x1a000
	s_add_i32 s33, s27, 0x8000
	s_add_i32 s34, s27, 0xa000
	global_load_lds_dwordx4 v[4:5], off
	v_lshl_add_u64 v[0:1], v[0:1], 0, s[14:15]
	s_mov_b32 m0, s33
	s_add_u32 s4, s22, 0xb0080
	global_load_lds_dwordx4 v[0:1], off
	v_lshl_add_u64 v[0:1], v[2:3], 0, s[14:15]
	s_mov_b32 m0, s34
	s_addc_u32 s5, s23, 0
	global_load_lds_dwordx4 v[0:1], off
	s_add_i32 m0, s27, 0x1c000
	v_lshl_add_u64 v[0:1], s[4:5], 0, v[156:157]
	global_load_lds_dwordx4 v[0:1], off
	v_lshl_add_u64 v[0:1], s[4:5], 0, v[160:161]
	s_add_i32 m0, s27, 0x1e000
	v_lshlrev_b32_e32 v3, 2, v153
	global_load_lds_dwordx4 v[0:1], off
	s_waitcnt vmcnt(8)
	s_barrier
	v_bfe_u32 v0, v153, 4, 2
	v_and_b32_e32 v1, 15, v153
	v_lshl_or_b32 v188, s2, 6, v1
	v_lshlrev_b32_e32 v2, 4, v0
	v_lshlrev_b32_e32 v4, 6, v153
	s_movk_i32 s2, 0x3c0
	v_lshl_or_b32 v1, v1, 6, v2
	v_and_b32_e32 v3, 32, v3
	v_and_or_b32 v2, v4, s2, v2
	v_bitop3_b32 v189, s3, v2, v3 bitop3:0xf6
	v_cmp_eq_u32_e64 s[2:3], 0, v0
	v_lshl_or_b32 v190, v0, 3, s18
	v_add_u16_e32 v0, v8, v9
	s_waitcnt vmcnt(6)
	s_cmpk_lt_u32 s6, 0x100
	v_lshrrev_b16_e32 v0, 1, v0
	v_bitop3_b32 v1, v1, s7, v3 bitop3:0xde
	s_cselect_b64 s[16:17], -1, 0
	v_add_lshl_u32 v162, v10, v0, 1
	v_add_lshl_u32 v164, v11, v0, 1
	s_add_i32 s38, 0, 0x10000
	s_add_i32 s39, 0, 0x14000
	v_mbcnt_lo_u32_b32 v0, -1, 0
	s_ashr_i32 s35, s76, 31
	s_mov_b32 s36, s76
	s_ashr_i32 s37, s97, 31
	v_mov_b32_e32 v163, v157
	v_mov_b32_e32 v165, v157
	v_mov_b64_e32 v[166:167], 0x200
	v_mov_b64_e32 v[168:169], 0x1ff
	v_add_u32_e32 v191, s38, v189
	v_add_u32_e32 v192, s39, v189
	v_add_u32_e32 v193, 0, v1
	v_mbcnt_hi_u32_b32 v194, -1, v0
	s_barrier
	s_branch .LBB0_705

; #define PG8_STAGE(bufoff, gbase, voff) do { _Pragma("unroll") for (int _i = 0; _i < 2; ++_i) \
;         __builtin_amdgcn_global_load_lds((const unsigned*)((const char*)(gbase) + (voff)[_i]), (LAS unsigned*)(lds + (bufoff) + ldsw + _i * 8192), 16, 0, 0); } while (0)
; #define PG8_WAIT_V(n) asm volatile("s_waitcnt vmcnt(" #n ")" ::: "memory")
; #define PG8_BAR __builtin_amdgcn_s_barrier()
; template <class Epi, class Sched, bool ALIGN_EPI>
; __device__ __forceinline__ void gemm_phase(LAS unsigned char* lds, const Gemm g, const Sched& S, const Epi& E) {
;     ...
;     const unsigned ldsw = (unsigned)wid * 1024u;
;     const int aoff = lds_byte(wr * 64 + fr, fq * 8), boff = lds_byte(wc * 32 + fr, fq * 8);
;     ...
;     PG8_STAGE(PG8_SB(0, 0), cB, voffB); PG8_STAGE(PG8_SB(0, 1), cB + hstepB, voffB); PG8_STAGE(PG8_SA(0, 0), cA, voffA); PG8_STAGE(PG8_SA(0, 1), cA + hstepA, voffA);
;     if (wr == 1) PG8_BAR;
;     PG8_WAIT_V(2); PG8_BAR;
;     PG8_STAGE(PG8_SB(1, 0), cB + kstep, voffB); PG8_STAGE(PG8_SA(1, 0), cA + kstep, voffA); PG8_STAGE(PG8_SB(1, 1), cB + hstepB + kstep, voffB);
;     PG8_WAIT_V(6); PG8_BAR;
.LBB0_868:
	s_add_u32 s12, s74, 0x3000000
	s_mov_b64 s[14:15], 0x80
	s_addc_u32 s13, s75, 0
	s_and_b32 s3, s2, 3
	s_add_i32 m0, s9, 0x18000
	v_lshl_add_u64 v[6:7], v[6:7], 0, s[14:15]
	s_lshl_b32 s18, s5, 13
	s_lshl_b32 s19, s3, 12
	global_load_lds_dwordx4 v[6:7], off
	v_lshl_add_u64 v[4:5], v[4:5], 0, s[14:15]
	s_add_i32 m0, s9, 0x1a000
	s_add_i32 s41, s9, 0x8000
	s_add_i32 s42, s9, 0xa000
	global_load_lds_dwordx4 v[4:5], off
	v_lshl_add_u64 v[0:1], v[0:1], 0, s[14:15]
	s_mov_b32 m0, s41
	s_add_u32 s16, s28, 0x40080
	global_load_lds_dwordx4 v[0:1], off
	v_lshl_add_u64 v[0:1], v[2:3], 0, s[14:15]
	s_mov_b32 m0, s42
	s_addc_u32 s17, s29, 0
	global_load_lds_dwordx4 v[0:1], off
	s_add_i32 m0, s9, 0x1c000
	v_lshl_add_u64 v[0:1], s[16:17], 0, v[130:131]
	global_load_lds_dwordx4 v[0:1], off
	v_lshl_add_u64 v[0:1], s[16:17], 0, v[134:135]
	s_add_i32 m0, s9, 0x1e000
	v_bfe_u32 v2, v153, 4, 2
	global_load_lds_dwordx4 v[0:1], off
	s_waitcnt vmcnt(8)
	s_barrier
	v_and_b32_e32 v1, 15, v153
	v_lshlrev_b32_e32 v3, 3, v2
	v_lshlrev_b32_e32 v2, 4, v2
	v_lshl_or_b32 v151, s5, 6, v1
	v_lshl_or_b32 v4, v1, 6, v2
	v_lshlrev_b32_e32 v1, 2, v1
	v_and_b32_e32 v5, 32, v1
	v_bitop3_b32 v4, v4, s18, v5 bitop3:0xde
	v_lshlrev_b32_e32 v5, 6, v153
	s_movk_i32 s16, 0x3c0
	s_cmpk_lt_u32 s4, 0x100
	v_lshrrev_b32_e32 v0, 4, v153
	v_and_or_b32 v2, v5, s16, v2
	s_cselect_b64 s[16:17], -1, 0
	s_lshl_b32 s4, s5, 8
	v_bitop3_b32 v0, s2, v0, 3 bitop3:0xa8
	s_add_i32 s4, s4, 0
	v_lshl_or_b32 v155, s3, 5, v3
	v_cmp_eq_u32_e64 s[2:3], 0, v0
	s_add_i32 s4, s4, 0x20000
	v_lshlrev_b32_e32 v0, 8, v153
	v_add_u32_e32 v157, s4, v1
	v_and_b32_e32 v0, 0x38000, v0
	v_lshlrev_b32_e32 v1, 11, v10
	v_or3_b32 v0, v8, v0, v1
	v_lshlrev_b32_e32 v5, 2, v153
	v_add_u32_e32 v138, v0, v9
	v_lshlrev_b32_e32 v0, 4, v11
	v_and_b32_e32 v5, 32, v5
	s_waitcnt vmcnt(6)
	v_and_b32_e32 v0, 0x78000, v0
	v_bitop3_b32 v154, s19, v2, v5 bitop3:0xf6
	v_or3_b32 v0, v8, v0, v1
	s_add_i32 s44, 0, 0x10000
	s_add_i32 s45, 0, 0x14000
	v_or_b32_e32 v156, 0xfffffb80, v155
	v_mov_b32_e32 v139, v137
	v_add_u32_e32 v140, v0, v9
	v_mov_b32_e32 v141, v137
	v_mov_b64_e32 v[142:143], 0x900
	v_mov_b64_e32 v[144:145], 0x8ff
	s_movk_i32 s43, 0x121
	v_add_u32_e32 v158, s44, v154
	v_add_u32_e32 v159, s45, v154
	v_add_u32_e32 v160, 0, v4
	s_movk_i32 s47, 0x2400
	s_mov_b32 s48, 0
	s_barrier
	s_branch .LBB0_871

; #define PG8_STAGE(bufoff, gbase, voff) do { _Pragma("unroll") for (int _i = 0; _i < 2; ++_i) \
;         __builtin_amdgcn_global_load_lds((const unsigned*)((const char*)(gbase) + (voff)[_i]), (LAS unsigned*)(lds + (bufoff) + ldsw + _i * 8192), 16, 0, 0); } while (0)
; #define PG8_WAIT_V(n) asm volatile("s_waitcnt vmcnt(" #n ")" ::: "memory")
; #define PG8_BAR __builtin_amdgcn_s_barrier()
; template <class Epi, class Sched, bool ALIGN_EPI>
; __device__ __forceinline__ void gemm_phase(LAS unsigned char* lds, const Gemm g, const Sched& S, const Epi& E) {
;     ...
;     const unsigned ldsw = (unsigned)wid * 1024u;
;     const int aoff = lds_byte(wr * 64 + fr, fq * 8), boff = lds_byte(wc * 32 + fr, fq * 8);
;     ...
;     PG8_STAGE(PG8_SB(0, 0), cB, voffB); PG8_STAGE(PG8_SB(0, 1), cB + hstepB, voffB); PG8_STAGE(PG8_SA(0, 0), cA, voffA); PG8_STAGE(PG8_SA(0, 1), cA + hstepA, voffA);
;     if (wr == 1) PG8_BAR;
;     PG8_WAIT_V(2); PG8_BAR;
;     PG8_STAGE(PG8_SB(1, 0), cB + kstep, voffB); PG8_STAGE(PG8_SA(1, 0), cA + kstep, voffA); PG8_STAGE(PG8_SB(1, 1), cB + hstepB + kstep, voffB);
;     PG8_WAIT_V(6); PG8_BAR;
.LBB0_1340:
	s_lshl_b32 s6, s6, 5
	s_and_b32 s12, s6, 0x60
	s_mov_b64 s[6:7], 0x80
	s_add_i32 m0, s39, 0x18000
	v_lshl_add_u64 v[6:7], v[6:7], 0, s[6:7]
	s_lshl_b32 s11, s3, 13
	s_lshl_b32 s13, s12, 7
	global_load_lds_dwordx4 v[6:7], off
	v_lshl_add_u64 v[4:5], v[4:5], 0, s[6:7]
	s_add_i32 m0, s39, 0x1a000
	s_add_i32 s44, s39, 0x8000
	s_add_i32 s45, s39, 0xa000
	global_load_lds_dwordx4 v[4:5], off
	v_lshl_add_u64 v[0:1], v[0:1], 0, s[6:7]
	s_mov_b32 m0, s44
	s_add_u32 s8, s24, 0x40080
	global_load_lds_dwordx4 v[0:1], off
	v_lshl_add_u64 v[0:1], v[2:3], 0, s[6:7]
	s_mov_b32 m0, s45
	s_addc_u32 s9, s25, 0
	global_load_lds_dwordx4 v[0:1], off
	s_add_i32 m0, s39, 0x1c000
	v_lshl_add_u64 v[0:1], s[8:9], 0, v[156:157]
	global_load_lds_dwordx4 v[0:1], off
	v_lshl_add_u64 v[0:1], s[8:9], 0, v[160:161]
	s_add_i32 m0, s39, 0x1e000
	s_sext_i32_i8 s23, s2
	global_load_lds_dwordx4 v[0:1], off
	s_waitcnt vmcnt(8)
	s_barrier
	v_and_b32_e32 v0, 15, v153
	v_lshlrev_b32_e32 v1, 1, v10
	v_lshlrev_b32_e32 v2, 2, v153
	v_lshlrev_b32_e32 v3, 6, v153
	s_movk_i32 s2, 0x3c0
	v_lshl_or_b32 v174, s3, 6, v0
	v_lshl_or_b32 v0, v0, 6, v1
	v_and_b32_e32 v2, 32, v2
	v_and_or_b32 v1, v3, s2, v1
	v_bitop3_b32 v175, s13, v1, v2 bitop3:0xf6
	v_lshlrev_b32_e32 v1, 4, v16
	v_bitop3_b32 v0, v0, s11, v2 bitop3:0xde
	v_and_b32_e32 v1, 0x78000, v1
	v_lshlrev_b32_e32 v2, 11, v14
	v_or3_b32 v1, v8, v1, v2
	v_add_u32_e32 v162, v1, v9
	v_lshlrev_b32_e32 v1, 8, v153
	v_and_b32_e32 v1, 0x38000, v1
	v_or3_b32 v1, v8, v1, v2
	v_add_u32_e32 v164, v1, v9
	v_add_u32_e32 v1, v15, v10
	v_add3_u32 v1, v1, v11, v12
	v_lshl_or_b32 v1, v1, 11, v8
	v_add_u32_e32 v166, v1, v9
	v_add_u32_e32 v1, v13, v10
	s_waitcnt vmcnt(6)
	s_cmpk_lt_u32 s10, 0x100
	v_add3_u32 v1, v1, v11, v12
	s_cselect_b64 s[10:11], -1, 0
	v_lshl_or_b32 v1, v1, 11, v8
	s_add_i32 s48, 0, 0x10000
	s_add_i32 s49, 0, 0x14000
	s_mov_b64 s[8:9], 0x40080
	s_ashr_i32 s46, s76, 31
	s_mov_b32 s47, s76
	v_or_b32_e32 v176, s12, v10
	v_mov_b32_e32 v163, v157
	v_mov_b32_e32 v165, v157
	v_mov_b32_e32 v167, v157
	v_add_u32_e32 v168, v1, v9
	v_mov_b32_e32 v169, v157
	v_mov_b64_e32 v[170:171], 0x200
	v_mov_b64_e32 v[172:173], 0x1ff
	v_add_u32_e32 v177, s48, v175
	v_add_u32_e32 v178, s49, v175
	v_add_u32_e32 v179, 0, v0
	s_add_i32 s50, s39, 0xc000
	s_add_i32 s51, s39, 0xe000
	s_mov_b64 s[12:13], 0x100
	s_mov_b64 s[14:15], 0x40100
	s_mov_b64 s[16:17], 0x180
	s_mov_b64 s[18:19], 0x40180
	s_movk_i32 s52, 0x2400
	s_barrier
	s_branch .LBB0_1343

; #define PG8_STAGE(bufoff, gbase, voff) do { _Pragma("unroll") for (int _i = 0; _i < 2; ++_i) \
;         __builtin_amdgcn_global_load_lds((const unsigned*)((const char*)(gbase) + (voff)[_i]), (LAS unsigned*)(lds + (bufoff) + ldsw + _i * 8192), 16, 0, 0); } while (0)
; #define PG8_WAIT_V(n) asm volatile("s_waitcnt vmcnt(" #n ")" ::: "memory")
; #define PG8_BAR __builtin_amdgcn_s_barrier()
; template <class Epi, class Sched, bool ALIGN_EPI>
; __device__ __forceinline__ void gemm_phase(LAS unsigned char* lds, const Gemm g, const Sched& S, const Epi& E) {
;     ...
;     const unsigned ldsw = (unsigned)wid * 1024u;
;     const int aoff = lds_byte(wr * 64 + fr, fq * 8), boff = lds_byte(wc * 32 + fr, fq * 8);
;     ...
;     PG8_STAGE(PG8_SB(0, 0), cB, voffB); PG8_STAGE(PG8_SB(0, 1), cB + hstepB, voffB); PG8_STAGE(PG8_SA(0, 0), cA, voffA); PG8_STAGE(PG8_SA(0, 1), cA + hstepA, voffA);
;     if (wr == 1) PG8_BAR;
;     PG8_WAIT_V(2); PG8_BAR;
;     PG8_STAGE(PG8_SB(1, 0), cB + kstep, voffB); PG8_STAGE(PG8_SA(1, 0), cA + kstep, voffA); PG8_STAGE(PG8_SB(1, 1), cB + hstepB + kstep, voffB);
;     PG8_WAIT_V(6); PG8_BAR;
.LBB0_1447:
	s_add_u32 s10, s74, 0x3800000
	s_addc_u32 s11, s75, 0
	s_add_u32 s12, s74, 0x19800000
	s_addc_u32 s13, s75, 0
	s_lshl_b32 s3, s3, 5
	s_mov_b64 s[14:15], 0x80
	s_and_b32 s18, s3, 0x60
	s_add_i32 m0, s29, 0x18000
	v_lshl_add_u64 v[6:7], v[6:7], 0, s[14:15]
	s_lshl_b32 s17, s2, 13
	s_lshl_b32 s3, s18, 7
	global_load_lds_dwordx4 v[6:7], off
	v_lshl_add_u64 v[4:5], v[4:5], 0, s[14:15]
	s_add_i32 m0, s29, 0x1a000
	s_add_i32 s42, s29, 0x8000
	s_add_i32 s43, s29, 0xa000
	global_load_lds_dwordx4 v[4:5], off
	v_lshl_add_u64 v[0:1], v[0:1], 0, s[14:15]
	s_mov_b32 m0, s42
	s_add_u32 s4, s34, 0x40080
	global_load_lds_dwordx4 v[0:1], off
	v_lshl_add_u64 v[0:1], v[2:3], 0, s[14:15]
	s_mov_b32 m0, s43
	s_addc_u32 s5, s35, 0
	global_load_lds_dwordx4 v[0:1], off
	s_add_i32 m0, s29, 0x1c000
	v_lshl_add_u64 v[0:1], s[4:5], 0, v[156:157]
	global_load_lds_dwordx4 v[0:1], off
	v_lshl_add_u64 v[0:1], s[4:5], 0, v[160:161]
	s_add_i32 m0, s29, 0x1e000
	v_lshlrev_b32_e32 v3, 2, v153
	global_load_lds_dwordx4 v[0:1], off
	s_waitcnt vmcnt(8)
	s_barrier
	v_bfe_u32 v0, v153, 4, 2
	v_and_b32_e32 v1, 15, v153
	v_lshl_or_b32 v188, s2, 6, v1
	v_lshlrev_b32_e32 v2, 4, v0
	v_lshlrev_b32_e32 v4, 6, v153
	s_movk_i32 s2, 0x3c0
	v_lshl_or_b32 v1, v1, 6, v2
	v_and_b32_e32 v3, 32, v3
	v_and_or_b32 v2, v4, s2, v2
	v_bitop3_b32 v189, s3, v2, v3 bitop3:0xf6
	v_cmp_eq_u32_e64 s[2:3], 0, v0
	v_lshl_or_b32 v190, v0, 3, s18
	v_lshlrev_b32_e32 v0, 9, v153
	v_and_b32_e32 v0, 0x70000, v0
	v_lshlrev_b32_e32 v2, 12, v10
	v_or3_b32 v0, v8, v0, v2
	v_add_u32_e32 v162, v0, v9
	v_lshlrev_b32_e32 v0, 5, v11
	v_and_b32_e32 v0, 0xf0000, v0
	s_waitcnt vmcnt(6)
	s_cmpk_lt_u32 s16, 0x100
	v_or3_b32 v0, v8, v0, v2
	v_bitop3_b32 v1, v1, s17, v3 bitop3:0xde
	s_cselect_b64 s[16:17], -1, 0
	v_add_u32_e32 v164, v0, v9
	s_add_i32 s47, 0, 0x10000
	s_add_i32 s48, 0, 0x14000
	v_mbcnt_lo_u32_b32 v0, -1, 0
	s_ashr_i32 s44, s76, 31
	s_mov_b32 s45, s76
	s_ashr_i32 s46, s97, 31
	v_mov_b32_e32 v163, v157
	v_mov_b32_e32 v165, v157
	v_mov_b64_e32 v[166:167], 0x200
	v_mov_b64_e32 v[168:169], 0x1ff
	v_add_u32_e32 v191, s47, v189
	v_add_u32_e32 v192, s48, v189
	v_add_u32_e32 v193, 0, v1
	v_mbcnt_hi_u32_b32 v194, -1, v0
	s_barrier
	s_branch .LBB0_1450

; #define PG8_STAGE(bufoff, gbase, voff) do { _Pragma("unroll") for (int _i = 0; _i < 2; ++_i) \
;         __builtin_amdgcn_global_load_lds((const unsigned*)((const char*)(gbase) + (voff)[_i]), (LAS unsigned*)(lds + (bufoff) + ldsw + _i * 8192), 16, 0, 0); } while (0)
; #define PG8_WAIT_V(n) asm volatile("s_waitcnt vmcnt(" #n ")" ::: "memory")
; #define PG8_BAR __builtin_amdgcn_s_barrier()
; template <class Epi, class Sched, bool ALIGN_EPI>
; __device__ __forceinline__ void gemm_phase(LAS unsigned char* lds, const Gemm g, const Sched& S, const Epi& E) {
;     ...
;     const unsigned ldsw = (unsigned)wid * 1024u;
;     const int aoff = lds_byte(wr * 64 + fr, fq * 8), boff = lds_byte(wc * 32 + fr, fq * 8);
;     ...
;     PG8_STAGE(PG8_SB(0, 0), cB, voffB); PG8_STAGE(PG8_SB(0, 1), cB + hstepB, voffB); PG8_STAGE(PG8_SA(0, 0), cA, voffA); PG8_STAGE(PG8_SA(0, 1), cA + hstepA, voffA);
;     if (wr == 1) PG8_BAR;
;     PG8_WAIT_V(2); PG8_BAR;
;     PG8_STAGE(PG8_SB(1, 0), cB + kstep, voffB); PG8_STAGE(PG8_SA(1, 0), cA + kstep, voffA); PG8_STAGE(PG8_SB(1, 1), cB + hstepB + kstep, voffB);
;     PG8_WAIT_V(6); PG8_BAR;
.LBB0_1607:
	s_lshl_b32 s6, s6, 5
	s_and_b32 s12, s6, 0x60
	s_mov_b64 s[6:7], 0x80
	s_add_i32 m0, s19, 0x18000
	v_lshl_add_u64 v[6:7], v[6:7], 0, s[6:7]
	s_lshl_b32 s9, s8, 13
	s_lshl_b32 s13, s12, 7
	global_load_lds_dwordx4 v[6:7], off
	v_lshl_add_u64 v[4:5], v[4:5], 0, s[6:7]
	s_add_i32 m0, s19, 0x1a000
	s_add_i32 s36, s19, 0x8000
	s_add_i32 s37, s19, 0xa000
	global_load_lds_dwordx4 v[4:5], off
	v_lshl_add_u64 v[0:1], v[0:1], 0, s[6:7]
	s_mov_b32 m0, s36
	s_add_u32 s10, s22, 0x40080
	global_load_lds_dwordx4 v[0:1], off
	v_lshl_add_u64 v[0:1], v[2:3], 0, s[6:7]
	s_mov_b32 m0, s37
	s_addc_u32 s11, s23, 0
	global_load_lds_dwordx4 v[0:1], off
	s_add_i32 m0, s19, 0x1c000
	v_lshl_add_u64 v[0:1], s[10:11], 0, v[132:133]
	global_load_lds_dwordx4 v[0:1], off
	v_lshl_add_u64 v[0:1], s[10:11], 0, v[128:129]
	s_add_i32 m0, s19, 0x1e000
	s_sext_i32_i8 s44, s2
	global_load_lds_dwordx4 v[0:1], off
	s_waitcnt vmcnt(8)
	s_barrier
	v_and_b32_e32 v0, 15, v153
	v_lshlrev_b32_e32 v1, 1, v11
	v_lshl_or_b32 v144, s8, 6, v0
	v_lshl_or_b32 v2, v0, 6, v1
	v_lshlrev_b32_e32 v0, 2, v0
	v_and_b32_e32 v3, 32, v0
	v_bitop3_b32 v2, v2, s9, v3 bitop3:0xde
	v_lshlrev_b32_e32 v3, 6, v153
	s_movk_i32 s2, 0x3c0
	v_and_or_b32 v1, v3, s2, v1
	s_lshl_b32 s2, s8, 8
	s_add_i32 s2, s2, 0
	v_lshlrev_b32_e32 v3, 2, v153
	s_add_i32 s2, s2, 0x20000
	v_and_b32_e32 v3, 32, v3
	v_add_u32_e32 v146, s2, v0
	v_lshlrev_b32_e32 v0, 8, v153
	v_bitop3_b32 v145, s13, v1, v3 bitop3:0xf6
	v_and_b32_e32 v0, 0x38000, v0
	v_lshlrev_b32_e32 v1, 11, v12
	v_or3_b32 v0, v9, v0, v1
	v_add_u32_e32 v136, v0, v10
	v_lshlrev_b32_e32 v0, 4, v8
	s_waitcnt vmcnt(6)
	s_cmpk_lt_u32 s3, 0x100
	v_and_b32_e32 v0, 0x78000, v0
	s_cselect_b64 s[8:9], -1, 0
	v_or3_b32 v0, v9, v0, v1
	s_add_i32 s38, 0, 0x10000
	s_add_i32 s39, 0, 0x14000
	v_or_b32_e32 v147, s12, v11
	v_mov_b32_e32 v137, v133
	v_add_u32_e32 v138, v0, v10
	v_mov_b32_e32 v139, v133
	v_mov_b64_e32 v[140:141], 0xb00
	v_mov_b64_e32 v[142:143], 0xaff
	v_add_u32_e32 v148, s38, v145
	v_add_u32_e32 v149, s39, v145
	v_add_u32_e32 v150, 0, v2
	s_movk_i32 s40, 0x1600
	s_mov_b32 s41, 0
	s_barrier
	s_branch .LBB0_1610

; #define PG8_STAGE(bufoff, gbase, voff) do { _Pragma("unroll") for (int _i = 0; _i < 2; ++_i) \
;         __builtin_amdgcn_global_load_lds((const unsigned*)((const char*)(gbase) + (voff)[_i]), (LAS unsigned*)(lds + (bufoff) + ldsw + _i * 8192), 16, 0, 0); } while (0)
; #define PG8_WAIT_V(n) asm volatile("s_waitcnt vmcnt(" #n ")" ::: "memory")
; #define PG8_BAR __builtin_amdgcn_s_barrier()
; template <class Epi, class Sched, bool ALIGN_EPI>
; __device__ __forceinline__ void gemm_phase(LAS unsigned char* lds, const Gemm g, const Sched& S, const Epi& E) {
;     ...
;     const unsigned ldsw = (unsigned)wid * 1024u;
;     const int aoff = lds_byte(wr * 64 + fr, fq * 8), boff = lds_byte(wc * 32 + fr, fq * 8);
;     ...
;     PG8_STAGE(PG8_SB(0, 0), cB, voffB); PG8_STAGE(PG8_SB(0, 1), cB + hstepB, voffB); PG8_STAGE(PG8_SA(0, 0), cA, voffA); PG8_STAGE(PG8_SA(0, 1), cA + hstepA, voffA);
;     if (wr == 1) PG8_BAR;
;     PG8_WAIT_V(2); PG8_BAR;
;     PG8_STAGE(PG8_SB(1, 0), cB + kstep, voffB); PG8_STAGE(PG8_SA(1, 0), cA + kstep, voffA); PG8_STAGE(PG8_SB(1, 1), cB + hstepB + kstep, voffB);
;     PG8_WAIT_V(6); PG8_BAR;
.LBB0_1708:
	s_add_u32 s10, s74, 0x19800000
	s_addc_u32 s11, s75, 0
	s_add_u32 s35, s74, 0x4000
	s_addc_u32 s36, s75, 0
	s_lshl_b32 s1, s1, 5
	s_and_b32 s6, s1, 0x60
	s_lshl_b32 s5, s0, 13
	s_lshl_b32 s1, s6, 7
	s_add_u32 s12, s74, 0x70000
	s_mov_b64 s[14:15], 0x80
	s_addc_u32 s13, s75, 0
	s_add_i32 m0, s29, 0x18000
	v_lshl_add_u64 v[6:7], v[6:7], 0, s[14:15]
	global_load_lds_dwordx4 v[6:7], off
	v_lshl_add_u64 v[4:5], v[4:5], 0, s[14:15]
	s_add_i32 m0, s29, 0x1a000
	s_add_i32 s37, s29, 0x8000
	s_add_i32 s38, s29, 0xa000
	global_load_lds_dwordx4 v[4:5], off
	v_lshl_add_u64 v[0:1], v[0:1], 0, s[14:15]
	s_mov_b32 m0, s37
	s_add_u32 s2, s22, 0xb0080
	global_load_lds_dwordx4 v[0:1], off
	v_lshl_add_u64 v[0:1], v[2:3], 0, s[14:15]
	s_mov_b32 m0, s38
	s_addc_u32 s3, s23, 0
	global_load_lds_dwordx4 v[0:1], off
	s_add_i32 m0, s29, 0x1c000
	v_lshl_add_u64 v[0:1], s[2:3], 0, v[156:157]
	global_load_lds_dwordx4 v[0:1], off
	v_lshl_add_u64 v[0:1], s[2:3], 0, v[160:161]
	s_add_i32 m0, s29, 0x1e000
	v_lshlrev_b32_e32 v3, 2, v153
	global_load_lds_dwordx4 v[0:1], off
	s_waitcnt vmcnt(8)
	s_barrier
	v_and_b32_e32 v0, 15, v153
	v_bfe_u32 v1, v153, 4, 2
	v_lshl_or_b32 v196, s0, 6, v0
	v_lshlrev_b32_e32 v2, 4, v1
	v_lshlrev_b32_e32 v4, 6, v153
	s_movk_i32 s0, 0x3c0
	v_lshl_or_b32 v0, v0, 6, v2
	v_and_b32_e32 v3, 32, v3
	v_and_or_b32 v2, v4, s0, v2
	v_bitop3_b32 v0, v0, s5, v3 bitop3:0xde
	v_bitop3_b32 v197, s1, v2, v3 bitop3:0xf6
	s_waitcnt vmcnt(6)
	s_cmpk_lt_u32 s4, 0x100
	v_cmp_eq_u32_e64 s[0:1], 0, v1
	v_lshl_or_b32 v198, v1, 3, s6
	v_add_u16_e32 v1, v8, v9
	s_cselect_b64 s[16:17], -1, 0
	v_lshrrev_b16_e32 v1, 1, v1
	s_add_i32 s41, 0, 0x10000
	s_add_i32 s42, 0, 0x14000
	v_add_u32_e32 v201, 0, v0
	v_mbcnt_lo_u32_b32 v0, -1, 0
	v_cmp_eq_u32_e64 s[2:3], 0, v152
	s_ashr_i32 s39, s76, 31
	s_ashr_i32 s40, s97, 31
	v_add_lshl_u32 v152, v10, v1, 1
	v_mov_b32_e32 v153, v157
	v_add_lshl_u32 v162, v11, v1, 1
	v_mov_b32_e32 v163, v157
	v_mov_b64_e32 v[164:165], 0x200
	v_mov_b64_e32 v[166:167], 0x1ff
	v_add_u32_e32 v199, s41, v197
	v_add_u32_e32 v200, s42, v197
	v_mbcnt_hi_u32_b32 v202, -1, v0
	v_mov_b32_e32 v203, 0x358637bd
	s_mov_b32 s43, 0x800000
	s_barrier
	s_branch .LBB0_1711
